# out-proj and FFN-down residual stores without nt hint (keep in cache for the following norm phase)
# speedup vs baseline: 1.0002x; 1.0002x over previous
.Lex_846:
	s_waitcnt lgkmcnt(0)
	v_add3_u32 v128, s20, v154, v160
	v_add3_u32 v130, s20, v154, v159
	v_add3_u32 v131, s20, v154, v158
	v_add3_u32 v146, s20, v154, v157
	v_add3_u32 v147, s20, v154, v156
	v_add3_u32 v149, s20, v154, v155
	v_add3_u32 v186, s20, v154, v153
	v_add3_u32 v187, s20, v150, v152
	v_add3_u32 v188, s21, v150, v151
	ds_read_b128 v[134:137], v128
	ds_read_b128 v[138:141], v130
	ds_read_b128 v[142:145], v131
	ds_read_b128 v[158:161], v146
	ds_read_b128 v[162:165], v147
	ds_read_b128 v[166:169], v149
	ds_read_b128 v[154:157], v186
	ds_read_b128 v[170:173], v187
	ds_read_b128 v[150:153], v188
	s_waitcnt lgkmcnt(0)
	v_mfma_f32_16x16x32_bf16 v[16:19], v[150:153], v[138:141], v[16:19]
	v_mfma_f32_16x16x32_bf16 v[174:177], v[150:153], v[134:137], v[36:39]
	s_nop 2
	ds_read_b128 v[36:39], v188 offset:2048
	s_waitcnt lgkmcnt(0)
	v_mfma_f32_16x16x32_bf16 v[8:11], v[36:39], v[138:141], v[8:11]
	v_mfma_f32_16x16x32_bf16 v[108:111], v[150:153], v[154:157], v[108:111]
	v_mfma_f32_16x16x32_bf16 v[60:63], v[150:153], v[158:161], v[60:63]
	v_mfma_f32_16x16x32_bf16 v[28:31], v[36:39], v[134:137], v[28:31]
	v_mfma_f32_16x16x32_bf16 v[104:107], v[36:39], v[154:157], v[104:107]
	v_mfma_f32_16x16x32_bf16 v[56:59], v[36:39], v[158:161], v[56:59]
	ds_read_b128 v[178:181], v188 offset:4096
	s_waitcnt lgkmcnt(0)
	v_mfma_f32_16x16x32_bf16 v[182:185], v[178:181], v[134:137], v[20:23]
	v_mfma_f32_16x16x32_bf16 v[100:103], v[178:181], v[154:157], v[100:103]
	v_mfma_f32_16x16x32_bf16 v[52:55], v[178:181], v[158:161], v[52:55]
	s_nop 0
	ds_read_b128 v[20:23], v188 offset:6144
	s_waitcnt lgkmcnt(0)
	v_mfma_f32_16x16x32_bf16 v[134:137], v[20:23], v[134:137], v[12:15]
	v_mfma_f32_16x16x32_bf16 v[12:15], v[20:23], v[170:173], v[112:115]
	v_mfma_f32_16x16x32_bf16 v[96:99], v[20:23], v[154:157], v[96:99]
	v_mfma_f32_16x16x32_bf16 v[112:115], v[20:23], v[162:165], v[64:67]
	v_mfma_f32_16x16x32_bf16 v[64:67], v[178:181], v[170:173], v[116:119]
	v_mfma_f32_16x16x32_bf16 v[116:119], v[178:181], v[162:165], v[68:71]
	v_mfma_f32_16x16x32_bf16 v[68:71], v[36:39], v[170:173], v[120:123]
	v_mfma_f32_16x16x32_bf16 v[120:123], v[36:39], v[162:165], v[72:75]
	v_mfma_f32_16x16x32_bf16 v[72:75], v[150:153], v[170:173], v[124:127]
	v_mfma_f32_16x16x32_bf16 v[124:127], v[150:153], v[162:165], v[76:79]
	v_mfma_f32_16x16x32_bf16 v[48:51], v[20:23], v[158:161], v[48:51]
	v_mfma_f32_16x16x32_bf16 v[154:157], v[150:153], v[142:145], v[44:47]
	v_mfma_f32_16x16x32_bf16 v[158:161], v[36:39], v[142:145], v[40:43]
	v_mfma_f32_16x16x32_bf16 v[162:165], v[178:181], v[142:145], v[32:35]
	v_mfma_f32_16x16x32_bf16 v[24:27], v[20:23], v[142:145], v[24:27]
	v_mfma_f32_16x16x32_bf16 v[142:145], v[178:181], v[138:141], v[4:7]
	v_mfma_f32_16x16x32_bf16 v[92:95], v[150:153], v[166:169], v[92:95]
	v_mfma_f32_16x16x32_bf16 v[88:91], v[36:39], v[166:169], v[88:91]
	v_mfma_f32_16x16x32_bf16 v[84:87], v[178:181], v[166:169], v[84:87]
	v_mfma_f32_16x16x32_bf16 v[80:83], v[20:23], v[166:169], v[80:83]
	v_mfma_f32_16x16x32_bf16 v[20:23], v[20:23], v[138:141], v[0:3]
	ds_read_b128 v[138:141], v188 offset:1024
	ds_read_b128 v[150:153], v188 offset:3072
	ds_read_b128 v[166:169], v188 offset:5120
	ds_read_b128 v[170:173], v188 offset:7168
	ds_read_b128 v[0:3], v187 offset:1024
	ds_read_b128 v[4:7], v186 offset:1024
	ds_read_b128 v[32:35], v149 offset:1024
	ds_read_b128 v[36:39], v147 offset:1024
	s_waitcnt lgkmcnt(3)
	v_mfma_f32_16x16x32_bf16 v[178:181], v[138:141], v[0:3], v[72:75]
	v_mfma_f32_16x16x32_bf16 v[186:189], v[150:153], v[0:3], v[68:71]
	v_mfma_f32_16x16x32_bf16 v[190:193], v[166:169], v[0:3], v[64:67]
	v_mfma_f32_16x16x32_bf16 v[194:197], v[170:173], v[0:3], v[12:15]
	ds_read_b128 v[0:3], v146 offset:1024
	s_waitcnt lgkmcnt(3)
	v_mfma_f32_16x16x32_bf16 v[108:111], v[138:141], v[4:7], v[108:111]
	v_mfma_f32_16x16x32_bf16 v[198:201], v[150:153], v[4:7], v[104:107]
	v_mfma_f32_16x16x32_bf16 v[202:205], v[166:169], v[4:7], v[100:103]
	v_mfma_f32_16x16x32_bf16 v[98:101], v[170:173], v[4:7], v[96:99]
	ds_read_b128 v[4:7], v131 offset:1024
	s_waitcnt lgkmcnt(3)
	v_mfma_f32_16x16x32_bf16 v[64:67], v[138:141], v[32:35], v[92:95]
	v_mfma_f32_16x16x32_bf16 v[68:71], v[150:153], v[32:35], v[88:91]
	v_mfma_f32_16x16x32_bf16 v[72:75], v[166:169], v[32:35], v[84:87]
	v_mfma_f32_16x16x32_bf16 v[76:79], v[170:173], v[32:35], v[80:83]
	ds_read_b128 v[12:15], v130 offset:1024
	s_waitcnt lgkmcnt(3)
	v_mfma_f32_16x16x32_bf16 v[80:83], v[138:141], v[36:39], v[124:127]
	v_mfma_f32_16x16x32_bf16 v[84:87], v[150:153], v[36:39], v[120:123]
	v_mfma_f32_16x16x32_bf16 v[88:91], v[166:169], v[36:39], v[116:119]
	v_mfma_f32_16x16x32_bf16 v[92:95], v[170:173], v[36:39], v[112:115]
	ds_read_b128 v[102:105], v128 offset:1024
	s_waitcnt lgkmcnt(3)
	v_mfma_f32_16x16x32_bf16 v[32:35], v[138:141], v[0:3], v[60:63]
	v_mfma_f32_16x16x32_bf16 v[36:39], v[150:153], v[0:3], v[56:59]
	v_mfma_f32_16x16x32_bf16 v[40:43], v[166:169], v[0:3], v[52:55]
	v_mfma_f32_16x16x32_bf16 v[44:47], v[170:173], v[0:3], v[48:51]
	s_waitcnt lgkmcnt(2)
	v_mfma_f32_16x16x32_bf16 v[48:51], v[138:141], v[4:7], v[154:157]
	v_mfma_f32_16x16x32_bf16 v[52:55], v[150:153], v[4:7], v[158:161]
	v_mfma_f32_16x16x32_bf16 v[56:59], v[166:169], v[4:7], v[162:165]
	v_mfma_f32_16x16x32_bf16 v[60:63], v[170:173], v[4:7], v[24:27]
	s_waitcnt lgkmcnt(1)
	v_mfma_f32_16x16x32_bf16 v[0:3], v[138:141], v[12:15], v[16:19]
	v_mfma_f32_16x16x32_bf16 v[4:7], v[150:153], v[12:15], v[8:11]
	v_mfma_f32_16x16x32_bf16 v[8:11], v[166:169], v[12:15], v[142:145]
	v_mfma_f32_16x16x32_bf16 v[12:15], v[170:173], v[12:15], v[20:23]
	s_waitcnt lgkmcnt(0)
	v_mfma_f32_16x16x32_bf16 v[16:19], v[138:141], v[102:105], v[174:177]
	v_mfma_f32_16x16x32_bf16 v[20:23], v[150:153], v[102:105], v[28:31]
	v_mfma_f32_16x16x32_bf16 v[24:27], v[166:169], v[102:105], v[182:185]
	v_mfma_f32_16x16x32_bf16 v[28:31], v[170:173], v[102:105], v[134:137]
	v_lshrrev_b32_e32 v96, 6, v148
	v_mul_lo_u32 v96, v96, s22
	v_mov_b32_e32 v97, s3
	v_add_u32_e32 v118, s20, v96
	v_lshlrev_b32_e32 v96, 2, v148
	s_waitcnt vmcnt(0)
	s_barrier
	v_and_b32_e32 v102, 63, v132
	v_lshrrev_b32_e32 v103, 6, v132
	v_and_b32_e32 v104, 15, v102
	v_lshrrev_b32_e32 v105, 4, v102
	v_mul_u32_u24_e32 v112, 0x2400, v103
	v_add_u32_e32 v112, 0x10000, v112
	v_mul_u32_u24_e32 v128, 0x110, v104
	v_lshl_add_u32 v128, v105, 4, v128
	v_add_u32_e32 v128, v128, v112
	v_mul_u32_u24_e32 v134, 0x110, v105
	v_lshl_add_u32 v134, v104, 4, v134
	v_add_u32_e32 v134, v134, v112
	v_lshrrev_b32_e32 v113, 2, v103
	v_lshl_add_u32 v113, v113, 7, v105
	v_add_u32_e32 v113, s14, v113
	v_and_b32_e32 v114, 3, v103
	v_lshlrev_b32_e32 v114, 6, v114
	v_lshl_add_u32 v114, v104, 2, v114
	v_add_u32_e32 v114, s12, v114
	v_mov_b32_e32 v130, 0x24000
	ds_read_b64 v[96:97], v130
	v_mov_b32_e32 v130, 0x240a0
	ds_read_b64 v[106:107], v130
	v_mov_b32_e32 v130, 0x240a8
	ds_read_b64 v[124:125], v130
	s_lshr_b32 s100, s14, 12
	s_mul_i32 s100, s100, 0x6000
	s_add_i32 s100, s100, 0x2282000
	s_mov_b64 s[98:99], 0x4000
	v_lshlrev_b32_e32 v130, 12, v113
	v_lshl_add_u32 v130, v114, 2, v130
	v_mov_b32_e32 v131, 0
	s_waitcnt lgkmcnt(0)
	v_lshl_add_u64 v[96:97], v[96:97], 0, v[130:131]
	v_lshl_add_u64 v[106:107], v[106:107], 0, v[130:131]
	v_lshl_add_u32 v130, v114, 2, s100
	v_lshl_add_u64 v[124:125], v[124:125], 0, v[130:131]
	global_load_dwordx4 v[124:127], v[124:125], off
	ds_write_b128 v128, v[178:181]
	ds_write_b128 v128, v[186:189] offset:64
	ds_write_b128 v128, v[190:193] offset:128
	ds_write_b128 v128, v[194:197] offset:192
	ds_write_b128 v128, v[108:111] offset:4352
	ds_write_b128 v128, v[198:201] offset:4416
	ds_write_b128 v128, v[202:205] offset:4480
	ds_write_b128 v128, v[98:101] offset:4544
	s_waitcnt lgkmcnt(0)
	global_load_dwordx4 v[102:105], v[96:97], off nt
	v_lshl_add_u64 v[96:97], v[96:97], 0, s[98:99]
	global_load_dwordx4 v[112:115], v[96:97], off nt
	v_lshl_add_u64 v[96:97], v[96:97], 0, s[98:99]
	global_load_dwordx4 v[116:119], v[96:97], off nt
	v_lshl_add_u64 v[96:97], v[96:97], 0, s[98:99]
	global_load_dwordx4 v[120:123], v[96:97], off nt
	v_lshl_add_u64 v[96:97], v[96:97], 0, s[98:99]
	global_load_dwordx4 v[178:181], v[96:97], off nt
	v_lshl_add_u64 v[96:97], v[96:97], 0, s[98:99]
	global_load_dwordx4 v[186:189], v[96:97], off nt
	v_lshl_add_u64 v[96:97], v[96:97], 0, s[98:99]
	global_load_dwordx4 v[190:193], v[96:97], off nt
	v_lshl_add_u64 v[96:97], v[96:97], 0, s[98:99]
	global_load_dwordx4 v[194:197], v[96:97], off nt
	v_lshl_add_u64 v[96:97], v[96:97], 0, s[98:99]
	ds_read_b128 v[240:243], v134
	s_waitcnt vmcnt(7) lgkmcnt(0)
	v_pk_fma_f32 v[104:105], v[242:243], v[126:127], v[104:105]
	v_pk_fma_f32 v[102:103], v[240:241], v[124:125], v[102:103]
	global_store_dwordx4 v[106:107], v[102:105], off
	v_lshl_add_u64 v[106:107], v[106:107], 0, s[98:99]
	ds_read_b128 v[240:243], v134 offset:1088
	s_waitcnt vmcnt(7) lgkmcnt(0)
	v_pk_fma_f32 v[114:115], v[242:243], v[126:127], v[114:115]
	v_pk_fma_f32 v[112:113], v[240:241], v[124:125], v[112:113]
	global_store_dwordx4 v[106:107], v[112:115], off
	v_lshl_add_u64 v[106:107], v[106:107], 0, s[98:99]
	ds_read_b128 v[240:243], v134 offset:2176
	s_waitcnt vmcnt(7) lgkmcnt(0)
	v_pk_fma_f32 v[118:119], v[242:243], v[126:127], v[118:119]
	v_pk_fma_f32 v[116:117], v[240:241], v[124:125], v[116:117]
	global_store_dwordx4 v[106:107], v[116:119], off
	v_lshl_add_u64 v[106:107], v[106:107], 0, s[98:99]
	ds_read_b128 v[240:243], v134 offset:3264
	s_waitcnt vmcnt(7) lgkmcnt(0)
	v_pk_fma_f32 v[122:123], v[242:243], v[126:127], v[122:123]
	v_pk_fma_f32 v[120:121], v[240:241], v[124:125], v[120:121]
	global_store_dwordx4 v[106:107], v[120:123], off
	v_lshl_add_u64 v[106:107], v[106:107], 0, s[98:99]
	global_load_dwordx4 v[102:105], v[96:97], off nt
	v_lshl_add_u64 v[96:97], v[96:97], 0, s[98:99]
	global_load_dwordx4 v[112:115], v[96:97], off nt
	v_lshl_add_u64 v[96:97], v[96:97], 0, s[98:99]
	global_load_dwordx4 v[116:119], v[96:97], off nt
	v_lshl_add_u64 v[96:97], v[96:97], 0, s[98:99]
	global_load_dwordx4 v[120:123], v[96:97], off nt
	v_lshl_add_u64 v[96:97], v[96:97], 0, s[98:99]
	ds_read_b128 v[240:243], v134 offset:4352
	s_waitcnt vmcnt(11) lgkmcnt(0)
	v_pk_fma_f32 v[180:181], v[242:243], v[126:127], v[180:181]
	v_pk_fma_f32 v[178:179], v[240:241], v[124:125], v[178:179]
	global_store_dwordx4 v[106:107], v[178:181], off
	v_lshl_add_u64 v[106:107], v[106:107], 0, s[98:99]
	ds_read_b128 v[240:243], v134 offset:5440
	s_waitcnt vmcnt(11) lgkmcnt(0)
	v_pk_fma_f32 v[188:189], v[242:243], v[126:127], v[188:189]
	v_pk_fma_f32 v[186:187], v[240:241], v[124:125], v[186:187]
	global_store_dwordx4 v[106:107], v[186:189], off
	v_lshl_add_u64 v[106:107], v[106:107], 0, s[98:99]
	ds_read_b128 v[240:243], v134 offset:6528
	s_waitcnt vmcnt(11) lgkmcnt(0)
	v_pk_fma_f32 v[192:193], v[242:243], v[126:127], v[192:193]
	v_pk_fma_f32 v[190:191], v[240:241], v[124:125], v[190:191]
	global_store_dwordx4 v[106:107], v[190:193], off
	v_lshl_add_u64 v[106:107], v[106:107], 0, s[98:99]
	ds_read_b128 v[240:243], v134 offset:7616
	s_waitcnt vmcnt(11) lgkmcnt(0)
	v_pk_fma_f32 v[196:197], v[242:243], v[126:127], v[196:197]
	v_pk_fma_f32 v[194:195], v[240:241], v[124:125], v[194:195]
	global_store_dwordx4 v[106:107], v[194:197], off
	v_lshl_add_u64 v[106:107], v[106:107], 0, s[98:99]
	ds_write_b128 v128, v[64:67]
	ds_write_b128 v128, v[68:71] offset:64
	ds_write_b128 v128, v[72:75] offset:128
	ds_write_b128 v128, v[76:79] offset:192
	ds_write_b128 v128, v[80:83] offset:4352
	ds_write_b128 v128, v[84:87] offset:4416
	ds_write_b128 v128, v[88:91] offset:4480
	ds_write_b128 v128, v[92:95] offset:4544
	global_load_dwordx4 v[178:181], v[96:97], off nt
	v_lshl_add_u64 v[96:97], v[96:97], 0, s[98:99]
	global_load_dwordx4 v[186:189], v[96:97], off nt
	v_lshl_add_u64 v[96:97], v[96:97], 0, s[98:99]
	global_load_dwordx4 v[190:193], v[96:97], off nt
	v_lshl_add_u64 v[96:97], v[96:97], 0, s[98:99]
	global_load_dwordx4 v[194:197], v[96:97], off nt
	v_lshl_add_u64 v[96:97], v[96:97], 0, s[98:99]
	ds_read_b128 v[240:243], v134
	s_waitcnt vmcnt(11) lgkmcnt(0)
	v_pk_fma_f32 v[104:105], v[242:243], v[126:127], v[104:105]
	v_pk_fma_f32 v[102:103], v[240:241], v[124:125], v[102:103]
	global_store_dwordx4 v[106:107], v[102:105], off
	v_lshl_add_u64 v[106:107], v[106:107], 0, s[98:99]
	ds_read_b128 v[240:243], v134 offset:1088
	s_waitcnt vmcnt(11) lgkmcnt(0)
	v_pk_fma_f32 v[114:115], v[242:243], v[126:127], v[114:115]
	v_pk_fma_f32 v[112:113], v[240:241], v[124:125], v[112:113]
	global_store_dwordx4 v[106:107], v[112:115], off
	v_lshl_add_u64 v[106:107], v[106:107], 0, s[98:99]
	ds_read_b128 v[240:243], v134 offset:2176
	s_waitcnt vmcnt(11) lgkmcnt(0)
	v_pk_fma_f32 v[118:119], v[242:243], v[126:127], v[118:119]
	v_pk_fma_f32 v[116:117], v[240:241], v[124:125], v[116:117]
	global_store_dwordx4 v[106:107], v[116:119], off
	v_lshl_add_u64 v[106:107], v[106:107], 0, s[98:99]
	ds_read_b128 v[240:243], v134 offset:3264
	s_waitcnt vmcnt(11) lgkmcnt(0)
	v_pk_fma_f32 v[122:123], v[242:243], v[126:127], v[122:123]
	v_pk_fma_f32 v[120:121], v[240:241], v[124:125], v[120:121]
	global_store_dwordx4 v[106:107], v[120:123], off
	v_lshl_add_u64 v[106:107], v[106:107], 0, s[98:99]
	global_load_dwordx4 v[102:105], v[96:97], off nt
	v_lshl_add_u64 v[96:97], v[96:97], 0, s[98:99]
	global_load_dwordx4 v[112:115], v[96:97], off nt
	v_lshl_add_u64 v[96:97], v[96:97], 0, s[98:99]
	global_load_dwordx4 v[116:119], v[96:97], off nt
	v_lshl_add_u64 v[96:97], v[96:97], 0, s[98:99]
	global_load_dwordx4 v[120:123], v[96:97], off nt
	v_lshl_add_u64 v[96:97], v[96:97], 0, s[98:99]
	ds_read_b128 v[240:243], v134 offset:4352
	s_waitcnt vmcnt(11) lgkmcnt(0)
	v_pk_fma_f32 v[180:181], v[242:243], v[126:127], v[180:181]
	v_pk_fma_f32 v[178:179], v[240:241], v[124:125], v[178:179]
	global_store_dwordx4 v[106:107], v[178:181], off
	v_lshl_add_u64 v[106:107], v[106:107], 0, s[98:99]
	ds_read_b128 v[240:243], v134 offset:5440
	s_waitcnt vmcnt(11) lgkmcnt(0)
	v_pk_fma_f32 v[188:189], v[242:243], v[126:127], v[188:189]
	v_pk_fma_f32 v[186:187], v[240:241], v[124:125], v[186:187]
	global_store_dwordx4 v[106:107], v[186:189], off
	v_lshl_add_u64 v[106:107], v[106:107], 0, s[98:99]
	ds_read_b128 v[240:243], v134 offset:6528
	s_waitcnt vmcnt(11) lgkmcnt(0)
	v_pk_fma_f32 v[192:193], v[242:243], v[126:127], v[192:193]
	v_pk_fma_f32 v[190:191], v[240:241], v[124:125], v[190:191]
	global_store_dwordx4 v[106:107], v[190:193], off
	v_lshl_add_u64 v[106:107], v[106:107], 0, s[98:99]
	ds_read_b128 v[240:243], v134 offset:7616
	s_waitcnt vmcnt(11) lgkmcnt(0)
	v_pk_fma_f32 v[196:197], v[242:243], v[126:127], v[196:197]
	v_pk_fma_f32 v[194:195], v[240:241], v[124:125], v[194:195]
	global_store_dwordx4 v[106:107], v[194:197], off
	v_lshl_add_u64 v[106:107], v[106:107], 0, s[98:99]
	ds_write_b128 v128, v[32:35]
	ds_write_b128 v128, v[36:39] offset:64
	ds_write_b128 v128, v[40:43] offset:128
	ds_write_b128 v128, v[44:47] offset:192
	ds_write_b128 v128, v[48:51] offset:4352
	ds_write_b128 v128, v[52:55] offset:4416
	ds_write_b128 v128, v[56:59] offset:4480
	ds_write_b128 v128, v[60:63] offset:4544
	global_load_dwordx4 v[178:181], v[96:97], off nt
	v_lshl_add_u64 v[96:97], v[96:97], 0, s[98:99]
	global_load_dwordx4 v[186:189], v[96:97], off nt
	v_lshl_add_u64 v[96:97], v[96:97], 0, s[98:99]
	global_load_dwordx4 v[190:193], v[96:97], off nt
	v_lshl_add_u64 v[96:97], v[96:97], 0, s[98:99]
	global_load_dwordx4 v[194:197], v[96:97], off nt
	v_lshl_add_u64 v[96:97], v[96:97], 0, s[98:99]
	ds_read_b128 v[240:243], v134
	s_waitcnt vmcnt(11) lgkmcnt(0)
	v_pk_fma_f32 v[104:105], v[242:243], v[126:127], v[104:105]
	v_pk_fma_f32 v[102:103], v[240:241], v[124:125], v[102:103]
	global_store_dwordx4 v[106:107], v[102:105], off
	v_lshl_add_u64 v[106:107], v[106:107], 0, s[98:99]
	ds_read_b128 v[240:243], v134 offset:1088
	s_waitcnt vmcnt(11) lgkmcnt(0)
	v_pk_fma_f32 v[114:115], v[242:243], v[126:127], v[114:115]
	v_pk_fma_f32 v[112:113], v[240:241], v[124:125], v[112:113]
	global_store_dwordx4 v[106:107], v[112:115], off
	v_lshl_add_u64 v[106:107], v[106:107], 0, s[98:99]
	ds_read_b128 v[240:243], v134 offset:2176
	s_waitcnt vmcnt(11) lgkmcnt(0)
	v_pk_fma_f32 v[118:119], v[242:243], v[126:127], v[118:119]
	v_pk_fma_f32 v[116:117], v[240:241], v[124:125], v[116:117]
	global_store_dwordx4 v[106:107], v[116:119], off
	v_lshl_add_u64 v[106:107], v[106:107], 0, s[98:99]
	ds_read_b128 v[240:243], v134 offset:3264
	s_waitcnt vmcnt(11) lgkmcnt(0)
	v_pk_fma_f32 v[122:123], v[242:243], v[126:127], v[122:123]
	v_pk_fma_f32 v[120:121], v[240:241], v[124:125], v[120:121]
	global_store_dwordx4 v[106:107], v[120:123], off
	v_lshl_add_u64 v[106:107], v[106:107], 0, s[98:99]
	global_load_dwordx4 v[102:105], v[96:97], off nt
	v_lshl_add_u64 v[96:97], v[96:97], 0, s[98:99]
	global_load_dwordx4 v[112:115], v[96:97], off nt
	v_lshl_add_u64 v[96:97], v[96:97], 0, s[98:99]
	global_load_dwordx4 v[116:119], v[96:97], off nt
	v_lshl_add_u64 v[96:97], v[96:97], 0, s[98:99]
	global_load_dwordx4 v[120:123], v[96:97], off nt
	v_lshl_add_u64 v[96:97], v[96:97], 0, s[98:99]
	ds_read_b128 v[240:243], v134 offset:4352
	s_waitcnt vmcnt(11) lgkmcnt(0)
	v_pk_fma_f32 v[180:181], v[242:243], v[126:127], v[180:181]
	v_pk_fma_f32 v[178:179], v[240:241], v[124:125], v[178:179]
	global_store_dwordx4 v[106:107], v[178:181], off
	v_lshl_add_u64 v[106:107], v[106:107], 0, s[98:99]
	ds_read_b128 v[240:243], v134 offset:5440
	s_waitcnt vmcnt(11) lgkmcnt(0)
	v_pk_fma_f32 v[188:189], v[242:243], v[126:127], v[188:189]
	v_pk_fma_f32 v[186:187], v[240:241], v[124:125], v[186:187]
	global_store_dwordx4 v[106:107], v[186:189], off
	v_lshl_add_u64 v[106:107], v[106:107], 0, s[98:99]
	ds_read_b128 v[240:243], v134 offset:6528
	s_waitcnt vmcnt(11) lgkmcnt(0)
	v_pk_fma_f32 v[192:193], v[242:243], v[126:127], v[192:193]
	v_pk_fma_f32 v[190:191], v[240:241], v[124:125], v[190:191]
	global_store_dwordx4 v[106:107], v[190:193], off
	v_lshl_add_u64 v[106:107], v[106:107], 0, s[98:99]
	ds_read_b128 v[240:243], v134 offset:7616
	s_waitcnt vmcnt(11) lgkmcnt(0)
	v_pk_fma_f32 v[196:197], v[242:243], v[126:127], v[196:197]
	v_pk_fma_f32 v[194:195], v[240:241], v[124:125], v[194:195]
	global_store_dwordx4 v[106:107], v[194:197], off
	v_lshl_add_u64 v[106:107], v[106:107], 0, s[98:99]
	ds_write_b128 v128, v[0:3]
	ds_write_b128 v128, v[4:7] offset:64
	ds_write_b128 v128, v[8:11] offset:128
	ds_write_b128 v128, v[12:15] offset:192
	ds_write_b128 v128, v[16:19] offset:4352
	ds_write_b128 v128, v[20:23] offset:4416
	ds_write_b128 v128, v[24:27] offset:4480
	ds_write_b128 v128, v[28:31] offset:4544
	global_load_dwordx4 v[178:181], v[96:97], off nt
	v_lshl_add_u64 v[96:97], v[96:97], 0, s[98:99]
	global_load_dwordx4 v[186:189], v[96:97], off nt
	v_lshl_add_u64 v[96:97], v[96:97], 0, s[98:99]
	global_load_dwordx4 v[190:193], v[96:97], off nt
	v_lshl_add_u64 v[96:97], v[96:97], 0, s[98:99]
	global_load_dwordx4 v[194:197], v[96:97], off nt
	v_lshl_add_u64 v[96:97], v[96:97], 0, s[98:99]
	ds_read_b128 v[240:243], v134
	s_waitcnt vmcnt(11) lgkmcnt(0)
	v_pk_fma_f32 v[104:105], v[242:243], v[126:127], v[104:105]
	v_pk_fma_f32 v[102:103], v[240:241], v[124:125], v[102:103]
	global_store_dwordx4 v[106:107], v[102:105], off
	v_lshl_add_u64 v[106:107], v[106:107], 0, s[98:99]
	ds_read_b128 v[240:243], v134 offset:1088
	s_waitcnt vmcnt(11) lgkmcnt(0)
	v_pk_fma_f32 v[114:115], v[242:243], v[126:127], v[114:115]
	v_pk_fma_f32 v[112:113], v[240:241], v[124:125], v[112:113]
	global_store_dwordx4 v[106:107], v[112:115], off
	v_lshl_add_u64 v[106:107], v[106:107], 0, s[98:99]
	ds_read_b128 v[240:243], v134 offset:2176
	s_waitcnt vmcnt(11) lgkmcnt(0)
	v_pk_fma_f32 v[118:119], v[242:243], v[126:127], v[118:119]
	v_pk_fma_f32 v[116:117], v[240:241], v[124:125], v[116:117]
	global_store_dwordx4 v[106:107], v[116:119], off
	v_lshl_add_u64 v[106:107], v[106:107], 0, s[98:99]
	ds_read_b128 v[240:243], v134 offset:3264
	s_waitcnt vmcnt(11) lgkmcnt(0)
	v_pk_fma_f32 v[122:123], v[242:243], v[126:127], v[122:123]
	v_pk_fma_f32 v[120:121], v[240:241], v[124:125], v[120:121]
	global_store_dwordx4 v[106:107], v[120:123], off
	v_lshl_add_u64 v[106:107], v[106:107], 0, s[98:99]
	ds_read_b128 v[240:243], v134 offset:4352
	s_waitcnt vmcnt(7) lgkmcnt(0)
	v_pk_fma_f32 v[180:181], v[242:243], v[126:127], v[180:181]
	v_pk_fma_f32 v[178:179], v[240:241], v[124:125], v[178:179]
	global_store_dwordx4 v[106:107], v[178:181], off
	v_lshl_add_u64 v[106:107], v[106:107], 0, s[98:99]
	ds_read_b128 v[240:243], v134 offset:5440
	s_waitcnt vmcnt(7) lgkmcnt(0)
	v_pk_fma_f32 v[188:189], v[242:243], v[126:127], v[188:189]
	v_pk_fma_f32 v[186:187], v[240:241], v[124:125], v[186:187]
	global_store_dwordx4 v[106:107], v[186:189], off
	v_lshl_add_u64 v[106:107], v[106:107], 0, s[98:99]
	ds_read_b128 v[240:243], v134 offset:6528
	s_waitcnt vmcnt(7) lgkmcnt(0)
	v_pk_fma_f32 v[192:193], v[242:243], v[126:127], v[192:193]
	v_pk_fma_f32 v[190:191], v[240:241], v[124:125], v[190:191]
	global_store_dwordx4 v[106:107], v[190:193], off
	v_lshl_add_u64 v[106:107], v[106:107], 0, s[98:99]
	ds_read_b128 v[240:243], v134 offset:7616
	s_waitcnt vmcnt(7) lgkmcnt(0)
	v_pk_fma_f32 v[196:197], v[242:243], v[126:127], v[196:197]
	v_pk_fma_f32 v[194:195], v[240:241], v[124:125], v[194:195]
	global_store_dwordx4 v[106:107], v[194:197], off
	v_lshl_add_u64 v[106:107], v[106:107], 0, s[98:99]
	s_add_i32 s27, s27, s40
	s_cmpk_gt_i32 s27, 0x1ff
	s_cbranch_scc0 .LBB0_845

.Lex_1138:
	s_waitcnt lgkmcnt(0)
	v_add3_u32 v128, s17, v154, v160
	v_add3_u32 v130, s17, v154, v159
	v_add3_u32 v131, s17, v154, v158
	v_add3_u32 v146, s17, v154, v157
	v_add3_u32 v147, s17, v154, v156
	v_add3_u32 v149, s17, v154, v155
	v_add3_u32 v186, s17, v154, v153
	v_add3_u32 v187, s17, v150, v152
	v_add3_u32 v188, s18, v150, v151
	ds_read_b128 v[134:137], v128
	ds_read_b128 v[138:141], v130
	ds_read_b128 v[142:145], v131
	ds_read_b128 v[158:161], v146
	ds_read_b128 v[162:165], v147
	ds_read_b128 v[166:169], v149
	ds_read_b128 v[154:157], v186
	ds_read_b128 v[170:173], v187
	ds_read_b128 v[150:153], v188
	s_waitcnt lgkmcnt(0)
	v_mfma_f32_16x16x32_bf16 v[16:19], v[150:153], v[138:141], v[16:19]
	v_mfma_f32_16x16x32_bf16 v[174:177], v[150:153], v[134:137], v[36:39]
	s_nop 2
	ds_read_b128 v[36:39], v188 offset:2048
	s_waitcnt lgkmcnt(0)
	v_mfma_f32_16x16x32_bf16 v[8:11], v[36:39], v[138:141], v[8:11]
	v_mfma_f32_16x16x32_bf16 v[108:111], v[150:153], v[154:157], v[108:111]
	v_mfma_f32_16x16x32_bf16 v[60:63], v[150:153], v[158:161], v[60:63]
	v_mfma_f32_16x16x32_bf16 v[28:31], v[36:39], v[134:137], v[28:31]
	v_mfma_f32_16x16x32_bf16 v[104:107], v[36:39], v[154:157], v[104:107]
	v_mfma_f32_16x16x32_bf16 v[56:59], v[36:39], v[158:161], v[56:59]
	ds_read_b128 v[178:181], v188 offset:4096
	s_waitcnt lgkmcnt(0)
	v_mfma_f32_16x16x32_bf16 v[182:185], v[178:181], v[134:137], v[20:23]
	v_mfma_f32_16x16x32_bf16 v[100:103], v[178:181], v[154:157], v[100:103]
	v_mfma_f32_16x16x32_bf16 v[52:55], v[178:181], v[158:161], v[52:55]
	s_nop 0
	ds_read_b128 v[20:23], v188 offset:6144
	s_waitcnt lgkmcnt(0)
	v_mfma_f32_16x16x32_bf16 v[134:137], v[20:23], v[134:137], v[12:15]
	v_mfma_f32_16x16x32_bf16 v[12:15], v[20:23], v[170:173], v[112:115]
	v_mfma_f32_16x16x32_bf16 v[96:99], v[20:23], v[154:157], v[96:99]
	v_mfma_f32_16x16x32_bf16 v[112:115], v[20:23], v[162:165], v[64:67]
	v_mfma_f32_16x16x32_bf16 v[64:67], v[178:181], v[170:173], v[116:119]
	v_mfma_f32_16x16x32_bf16 v[116:119], v[178:181], v[162:165], v[68:71]
	v_mfma_f32_16x16x32_bf16 v[68:71], v[36:39], v[170:173], v[120:123]
	v_mfma_f32_16x16x32_bf16 v[120:123], v[36:39], v[162:165], v[72:75]
	v_mfma_f32_16x16x32_bf16 v[72:75], v[150:153], v[170:173], v[124:127]
	v_mfma_f32_16x16x32_bf16 v[124:127], v[150:153], v[162:165], v[76:79]
	v_mfma_f32_16x16x32_bf16 v[48:51], v[20:23], v[158:161], v[48:51]
	v_mfma_f32_16x16x32_bf16 v[154:157], v[150:153], v[142:145], v[44:47]
	v_mfma_f32_16x16x32_bf16 v[158:161], v[36:39], v[142:145], v[40:43]
	v_mfma_f32_16x16x32_bf16 v[162:165], v[178:181], v[142:145], v[32:35]
	v_mfma_f32_16x16x32_bf16 v[24:27], v[20:23], v[142:145], v[24:27]
	v_mfma_f32_16x16x32_bf16 v[142:145], v[178:181], v[138:141], v[4:7]
	v_mfma_f32_16x16x32_bf16 v[92:95], v[150:153], v[166:169], v[92:95]
	v_mfma_f32_16x16x32_bf16 v[88:91], v[36:39], v[166:169], v[88:91]
	v_mfma_f32_16x16x32_bf16 v[84:87], v[178:181], v[166:169], v[84:87]
	v_mfma_f32_16x16x32_bf16 v[80:83], v[20:23], v[166:169], v[80:83]
	v_mfma_f32_16x16x32_bf16 v[20:23], v[20:23], v[138:141], v[0:3]
	ds_read_b128 v[138:141], v188 offset:1024
	ds_read_b128 v[150:153], v188 offset:3072
	ds_read_b128 v[166:169], v188 offset:5120
	ds_read_b128 v[170:173], v188 offset:7168
	ds_read_b128 v[0:3], v187 offset:1024
	ds_read_b128 v[4:7], v186 offset:1024
	ds_read_b128 v[32:35], v149 offset:1024
	ds_read_b128 v[36:39], v147 offset:1024
	s_waitcnt lgkmcnt(3)
	v_mfma_f32_16x16x32_bf16 v[178:181], v[138:141], v[0:3], v[72:75]
	v_mfma_f32_16x16x32_bf16 v[186:189], v[150:153], v[0:3], v[68:71]
	v_mfma_f32_16x16x32_bf16 v[190:193], v[166:169], v[0:3], v[64:67]
	v_mfma_f32_16x16x32_bf16 v[194:197], v[170:173], v[0:3], v[12:15]
	ds_read_b128 v[0:3], v146 offset:1024
	s_waitcnt lgkmcnt(3)
	v_mfma_f32_16x16x32_bf16 v[108:111], v[138:141], v[4:7], v[108:111]
	v_mfma_f32_16x16x32_bf16 v[104:107], v[150:153], v[4:7], v[104:107]
	v_mfma_f32_16x16x32_bf16 v[198:201], v[166:169], v[4:7], v[100:103]
	v_mfma_f32_16x16x32_bf16 v[96:99], v[170:173], v[4:7], v[96:99]
	ds_read_b128 v[4:7], v131 offset:1024
	s_waitcnt lgkmcnt(3)
	v_mfma_f32_16x16x32_bf16 v[64:67], v[138:141], v[32:35], v[92:95]
	v_mfma_f32_16x16x32_bf16 v[68:71], v[150:153], v[32:35], v[88:91]
	v_mfma_f32_16x16x32_bf16 v[72:75], v[166:169], v[32:35], v[84:87]
	v_mfma_f32_16x16x32_bf16 v[76:79], v[170:173], v[32:35], v[80:83]
	ds_read_b128 v[12:15], v130 offset:1024
	s_waitcnt lgkmcnt(3)
	v_mfma_f32_16x16x32_bf16 v[80:83], v[138:141], v[36:39], v[124:127]
	v_mfma_f32_16x16x32_bf16 v[84:87], v[150:153], v[36:39], v[120:123]
	v_mfma_f32_16x16x32_bf16 v[88:91], v[166:169], v[36:39], v[116:119]
	v_mfma_f32_16x16x32_bf16 v[92:95], v[170:173], v[36:39], v[112:115]
	ds_read_b128 v[100:103], v128 offset:1024
	s_waitcnt lgkmcnt(3)
	v_mfma_f32_16x16x32_bf16 v[32:35], v[138:141], v[0:3], v[60:63]
	v_mfma_f32_16x16x32_bf16 v[36:39], v[150:153], v[0:3], v[56:59]
	v_mfma_f32_16x16x32_bf16 v[40:43], v[166:169], v[0:3], v[52:55]
	v_mfma_f32_16x16x32_bf16 v[44:47], v[170:173], v[0:3], v[48:51]
	s_waitcnt lgkmcnt(2)
	v_mfma_f32_16x16x32_bf16 v[48:51], v[138:141], v[4:7], v[154:157]
	v_mfma_f32_16x16x32_bf16 v[52:55], v[150:153], v[4:7], v[158:161]
	v_mfma_f32_16x16x32_bf16 v[56:59], v[166:169], v[4:7], v[162:165]
	v_mfma_f32_16x16x32_bf16 v[60:63], v[170:173], v[4:7], v[24:27]
	s_waitcnt lgkmcnt(1)
	v_mfma_f32_16x16x32_bf16 v[0:3], v[138:141], v[12:15], v[16:19]
	v_mfma_f32_16x16x32_bf16 v[4:7], v[150:153], v[12:15], v[8:11]
	v_mfma_f32_16x16x32_bf16 v[8:11], v[166:169], v[12:15], v[142:145]
	v_mfma_f32_16x16x32_bf16 v[12:15], v[170:173], v[12:15], v[20:23]
	s_waitcnt lgkmcnt(0)
	v_mfma_f32_16x16x32_bf16 v[16:19], v[138:141], v[100:103], v[174:177]
	v_mfma_f32_16x16x32_bf16 v[20:23], v[150:153], v[100:103], v[28:31]
	v_mfma_f32_16x16x32_bf16 v[24:27], v[166:169], v[100:103], v[182:185]
	v_mfma_f32_16x16x32_bf16 v[28:31], v[170:173], v[100:103], v[134:137]
	v_mov_b32_e32 v102, s3
	s_waitcnt vmcnt(0)
	s_barrier
	v_and_b32_e32 v100, 63, v132
	v_lshrrev_b32_e32 v101, 6, v132
	v_and_b32_e32 v102, 15, v100
	v_lshrrev_b32_e32 v103, 4, v100
	v_mul_u32_u24_e32 v112, 0x2400, v101
	v_add_u32_e32 v112, 0x10000, v112
	v_mul_u32_u24_e32 v124, 0x110, v102
	v_lshl_add_u32 v124, v103, 4, v124
	v_add_u32_e32 v124, v124, v112
	v_mul_u32_u24_e32 v128, 0x110, v103
	v_lshl_add_u32 v128, v102, 4, v128
	v_add_u32_e32 v128, v128, v112
	v_lshrrev_b32_e32 v113, 2, v101
	v_lshl_add_u32 v113, v113, 7, v103
	v_add_u32_e32 v113, s24, v113
	v_and_b32_e32 v114, 3, v101
	v_lshlrev_b32_e32 v114, 6, v114
	v_lshl_add_u32 v114, v102, 2, v114
	v_add_u32_e32 v114, s10, v114
	v_mov_b32_e32 v252, 0x240a0
	ds_read_b64 v[248:249], v252
	v_mov_b32_e32 v252, 0x240a0
	ds_read_b64 v[250:251], v252
	v_mov_b32_e32 v252, 0x240a8
	ds_read_b64 v[240:241], v252
	s_lshr_b32 s100, s24, 12
	s_mul_i32 s100, s100, 0x6000
	s_add_i32 s100, s100, 0x2285000
	s_mov_b64 s[98:99], 0x4000
	v_lshlrev_b32_e32 v252, 12, v113
	v_lshl_add_u32 v252, v114, 2, v252
	v_mov_b32_e32 v253, 0
	s_waitcnt lgkmcnt(0)
	v_lshl_add_u64 v[248:249], v[248:249], 0, v[252:253]
	v_lshl_add_u64 v[250:251], v[250:251], 0, v[252:253]
	v_lshl_add_u32 v252, v114, 2, s100
	v_lshl_add_u64 v[240:241], v[240:241], 0, v[252:253]
	global_load_dwordx4 v[240:243], v[240:241], off
	ds_write_b128 v124, v[178:181]
	ds_write_b128 v124, v[186:189] offset:64
	ds_write_b128 v124, v[190:193] offset:128
	ds_write_b128 v124, v[194:197] offset:192
	ds_write_b128 v124, v[108:111] offset:4352
	ds_write_b128 v124, v[104:107] offset:4416
	ds_write_b128 v124, v[198:201] offset:4480
	ds_write_b128 v124, v[96:99] offset:4544
	s_waitcnt lgkmcnt(0)
	global_load_dwordx4 v[100:103], v[248:249], off nt
	v_lshl_add_u64 v[248:249], v[248:249], 0, s[98:99]
	global_load_dwordx4 v[112:115], v[248:249], off nt
	v_lshl_add_u64 v[248:249], v[248:249], 0, s[98:99]
	global_load_dwordx4 v[116:119], v[248:249], off nt
	v_lshl_add_u64 v[248:249], v[248:249], 0, s[98:99]
	global_load_dwordx4 v[120:123], v[248:249], off nt
	v_lshl_add_u64 v[248:249], v[248:249], 0, s[98:99]
	global_load_dwordx4 v[178:181], v[248:249], off nt
	v_lshl_add_u64 v[248:249], v[248:249], 0, s[98:99]
	global_load_dwordx4 v[186:189], v[248:249], off nt
	v_lshl_add_u64 v[248:249], v[248:249], 0, s[98:99]
	global_load_dwordx4 v[190:193], v[248:249], off nt
	v_lshl_add_u64 v[248:249], v[248:249], 0, s[98:99]
	global_load_dwordx4 v[194:197], v[248:249], off nt
	v_lshl_add_u64 v[248:249], v[248:249], 0, s[98:99]
	ds_read_b128 v[244:247], v128
	s_waitcnt vmcnt(7) lgkmcnt(0)
	v_pk_fma_f32 v[102:103], v[246:247], v[242:243], v[102:103]
	v_pk_fma_f32 v[100:101], v[244:245], v[240:241], v[100:101]
	global_store_dwordx4 v[250:251], v[100:103], off
	v_lshl_add_u64 v[250:251], v[250:251], 0, s[98:99]
	ds_read_b128 v[244:247], v128 offset:1088
	s_waitcnt vmcnt(7) lgkmcnt(0)
	v_pk_fma_f32 v[114:115], v[246:247], v[242:243], v[114:115]
	v_pk_fma_f32 v[112:113], v[244:245], v[240:241], v[112:113]
	global_store_dwordx4 v[250:251], v[112:115], off
	v_lshl_add_u64 v[250:251], v[250:251], 0, s[98:99]
	ds_read_b128 v[244:247], v128 offset:2176
	s_waitcnt vmcnt(7) lgkmcnt(0)
	v_pk_fma_f32 v[118:119], v[246:247], v[242:243], v[118:119]
	v_pk_fma_f32 v[116:117], v[244:245], v[240:241], v[116:117]
	global_store_dwordx4 v[250:251], v[116:119], off
	v_lshl_add_u64 v[250:251], v[250:251], 0, s[98:99]
	ds_read_b128 v[244:247], v128 offset:3264
	s_waitcnt vmcnt(7) lgkmcnt(0)
	v_pk_fma_f32 v[122:123], v[246:247], v[242:243], v[122:123]
	v_pk_fma_f32 v[120:121], v[244:245], v[240:241], v[120:121]
	global_store_dwordx4 v[250:251], v[120:123], off
	v_lshl_add_u64 v[250:251], v[250:251], 0, s[98:99]
	global_load_dwordx4 v[100:103], v[248:249], off nt
	v_lshl_add_u64 v[248:249], v[248:249], 0, s[98:99]
	global_load_dwordx4 v[112:115], v[248:249], off nt
	v_lshl_add_u64 v[248:249], v[248:249], 0, s[98:99]
	global_load_dwordx4 v[116:119], v[248:249], off nt
	v_lshl_add_u64 v[248:249], v[248:249], 0, s[98:99]
	global_load_dwordx4 v[120:123], v[248:249], off nt
	v_lshl_add_u64 v[248:249], v[248:249], 0, s[98:99]
	ds_read_b128 v[244:247], v128 offset:4352
	s_waitcnt vmcnt(11) lgkmcnt(0)
	v_pk_fma_f32 v[180:181], v[246:247], v[242:243], v[180:181]
	v_pk_fma_f32 v[178:179], v[244:245], v[240:241], v[178:179]
	global_store_dwordx4 v[250:251], v[178:181], off
	v_lshl_add_u64 v[250:251], v[250:251], 0, s[98:99]
	ds_read_b128 v[244:247], v128 offset:5440
	s_waitcnt vmcnt(11) lgkmcnt(0)
	v_pk_fma_f32 v[188:189], v[246:247], v[242:243], v[188:189]
	v_pk_fma_f32 v[186:187], v[244:245], v[240:241], v[186:187]
	global_store_dwordx4 v[250:251], v[186:189], off
	v_lshl_add_u64 v[250:251], v[250:251], 0, s[98:99]
	ds_read_b128 v[244:247], v128 offset:6528
	s_waitcnt vmcnt(11) lgkmcnt(0)
	v_pk_fma_f32 v[192:193], v[246:247], v[242:243], v[192:193]
	v_pk_fma_f32 v[190:191], v[244:245], v[240:241], v[190:191]
	global_store_dwordx4 v[250:251], v[190:193], off
	v_lshl_add_u64 v[250:251], v[250:251], 0, s[98:99]
	ds_read_b128 v[244:247], v128 offset:7616
	s_waitcnt vmcnt(11) lgkmcnt(0)
	v_pk_fma_f32 v[196:197], v[246:247], v[242:243], v[196:197]
	v_pk_fma_f32 v[194:195], v[244:245], v[240:241], v[194:195]
	global_store_dwordx4 v[250:251], v[194:197], off
	v_lshl_add_u64 v[250:251], v[250:251], 0, s[98:99]
	ds_write_b128 v124, v[64:67]
	ds_write_b128 v124, v[68:71] offset:64
	ds_write_b128 v124, v[72:75] offset:128
	ds_write_b128 v124, v[76:79] offset:192
	ds_write_b128 v124, v[80:83] offset:4352
	ds_write_b128 v124, v[84:87] offset:4416
	ds_write_b128 v124, v[88:91] offset:4480
	ds_write_b128 v124, v[92:95] offset:4544
	global_load_dwordx4 v[178:181], v[248:249], off nt
	v_lshl_add_u64 v[248:249], v[248:249], 0, s[98:99]
	global_load_dwordx4 v[186:189], v[248:249], off nt
	v_lshl_add_u64 v[248:249], v[248:249], 0, s[98:99]
	global_load_dwordx4 v[190:193], v[248:249], off nt
	v_lshl_add_u64 v[248:249], v[248:249], 0, s[98:99]
	global_load_dwordx4 v[194:197], v[248:249], off nt
	v_lshl_add_u64 v[248:249], v[248:249], 0, s[98:99]
	ds_read_b128 v[244:247], v128
	s_waitcnt vmcnt(11) lgkmcnt(0)
	v_pk_fma_f32 v[102:103], v[246:247], v[242:243], v[102:103]
	v_pk_fma_f32 v[100:101], v[244:245], v[240:241], v[100:101]
	global_store_dwordx4 v[250:251], v[100:103], off
	v_lshl_add_u64 v[250:251], v[250:251], 0, s[98:99]
	ds_read_b128 v[244:247], v128 offset:1088
	s_waitcnt vmcnt(11) lgkmcnt(0)
	v_pk_fma_f32 v[114:115], v[246:247], v[242:243], v[114:115]
	v_pk_fma_f32 v[112:113], v[244:245], v[240:241], v[112:113]
	global_store_dwordx4 v[250:251], v[112:115], off
	v_lshl_add_u64 v[250:251], v[250:251], 0, s[98:99]
	ds_read_b128 v[244:247], v128 offset:2176
	s_waitcnt vmcnt(11) lgkmcnt(0)
	v_pk_fma_f32 v[118:119], v[246:247], v[242:243], v[118:119]
	v_pk_fma_f32 v[116:117], v[244:245], v[240:241], v[116:117]
	global_store_dwordx4 v[250:251], v[116:119], off
	v_lshl_add_u64 v[250:251], v[250:251], 0, s[98:99]
	ds_read_b128 v[244:247], v128 offset:3264
	s_waitcnt vmcnt(11) lgkmcnt(0)
	v_pk_fma_f32 v[122:123], v[246:247], v[242:243], v[122:123]
	v_pk_fma_f32 v[120:121], v[244:245], v[240:241], v[120:121]
	global_store_dwordx4 v[250:251], v[120:123], off
	v_lshl_add_u64 v[250:251], v[250:251], 0, s[98:99]
	global_load_dwordx4 v[100:103], v[248:249], off nt
	v_lshl_add_u64 v[248:249], v[248:249], 0, s[98:99]
	global_load_dwordx4 v[112:115], v[248:249], off nt
	v_lshl_add_u64 v[248:249], v[248:249], 0, s[98:99]
	global_load_dwordx4 v[116:119], v[248:249], off nt
	v_lshl_add_u64 v[248:249], v[248:249], 0, s[98:99]
	global_load_dwordx4 v[120:123], v[248:249], off nt
	v_lshl_add_u64 v[248:249], v[248:249], 0, s[98:99]
	ds_read_b128 v[244:247], v128 offset:4352
	s_waitcnt vmcnt(11) lgkmcnt(0)
	v_pk_fma_f32 v[180:181], v[246:247], v[242:243], v[180:181]
	v_pk_fma_f32 v[178:179], v[244:245], v[240:241], v[178:179]
	global_store_dwordx4 v[250:251], v[178:181], off
	v_lshl_add_u64 v[250:251], v[250:251], 0, s[98:99]
	ds_read_b128 v[244:247], v128 offset:5440
	s_waitcnt vmcnt(11) lgkmcnt(0)
	v_pk_fma_f32 v[188:189], v[246:247], v[242:243], v[188:189]
	v_pk_fma_f32 v[186:187], v[244:245], v[240:241], v[186:187]
	global_store_dwordx4 v[250:251], v[186:189], off
	v_lshl_add_u64 v[250:251], v[250:251], 0, s[98:99]
	ds_read_b128 v[244:247], v128 offset:6528
	s_waitcnt vmcnt(11) lgkmcnt(0)
	v_pk_fma_f32 v[192:193], v[246:247], v[242:243], v[192:193]
	v_pk_fma_f32 v[190:191], v[244:245], v[240:241], v[190:191]
	global_store_dwordx4 v[250:251], v[190:193], off
	v_lshl_add_u64 v[250:251], v[250:251], 0, s[98:99]
	ds_read_b128 v[244:247], v128 offset:7616
	s_waitcnt vmcnt(11) lgkmcnt(0)
	v_pk_fma_f32 v[196:197], v[246:247], v[242:243], v[196:197]
	v_pk_fma_f32 v[194:195], v[244:245], v[240:241], v[194:195]
	global_store_dwordx4 v[250:251], v[194:197], off
	v_lshl_add_u64 v[250:251], v[250:251], 0, s[98:99]
	ds_write_b128 v124, v[32:35]
	ds_write_b128 v124, v[36:39] offset:64
	ds_write_b128 v124, v[40:43] offset:128
	ds_write_b128 v124, v[44:47] offset:192
	ds_write_b128 v124, v[48:51] offset:4352
	ds_write_b128 v124, v[52:55] offset:4416
	ds_write_b128 v124, v[56:59] offset:4480
	ds_write_b128 v124, v[60:63] offset:4544
	global_load_dwordx4 v[178:181], v[248:249], off nt
	v_lshl_add_u64 v[248:249], v[248:249], 0, s[98:99]
	global_load_dwordx4 v[186:189], v[248:249], off nt
	v_lshl_add_u64 v[248:249], v[248:249], 0, s[98:99]
	global_load_dwordx4 v[190:193], v[248:249], off nt
	v_lshl_add_u64 v[248:249], v[248:249], 0, s[98:99]
	global_load_dwordx4 v[194:197], v[248:249], off nt
	v_lshl_add_u64 v[248:249], v[248:249], 0, s[98:99]
	ds_read_b128 v[244:247], v128
	s_waitcnt vmcnt(11) lgkmcnt(0)
	v_pk_fma_f32 v[102:103], v[246:247], v[242:243], v[102:103]
	v_pk_fma_f32 v[100:101], v[244:245], v[240:241], v[100:101]
	global_store_dwordx4 v[250:251], v[100:103], off
	v_lshl_add_u64 v[250:251], v[250:251], 0, s[98:99]
	ds_read_b128 v[244:247], v128 offset:1088
	s_waitcnt vmcnt(11) lgkmcnt(0)
	v_pk_fma_f32 v[114:115], v[246:247], v[242:243], v[114:115]
	v_pk_fma_f32 v[112:113], v[244:245], v[240:241], v[112:113]
	global_store_dwordx4 v[250:251], v[112:115], off
	v_lshl_add_u64 v[250:251], v[250:251], 0, s[98:99]
	ds_read_b128 v[244:247], v128 offset:2176
	s_waitcnt vmcnt(11) lgkmcnt(0)
	v_pk_fma_f32 v[118:119], v[246:247], v[242:243], v[118:119]
	v_pk_fma_f32 v[116:117], v[244:245], v[240:241], v[116:117]
	global_store_dwordx4 v[250:251], v[116:119], off
	v_lshl_add_u64 v[250:251], v[250:251], 0, s[98:99]
	ds_read_b128 v[244:247], v128 offset:3264
	s_waitcnt vmcnt(11) lgkmcnt(0)
	v_pk_fma_f32 v[122:123], v[246:247], v[242:243], v[122:123]
	v_pk_fma_f32 v[120:121], v[244:245], v[240:241], v[120:121]
	global_store_dwordx4 v[250:251], v[120:123], off
	v_lshl_add_u64 v[250:251], v[250:251], 0, s[98:99]
	global_load_dwordx4 v[100:103], v[248:249], off nt
	v_lshl_add_u64 v[248:249], v[248:249], 0, s[98:99]
	global_load_dwordx4 v[112:115], v[248:249], off nt
	v_lshl_add_u64 v[248:249], v[248:249], 0, s[98:99]
	global_load_dwordx4 v[116:119], v[248:249], off nt
	v_lshl_add_u64 v[248:249], v[248:249], 0, s[98:99]
	global_load_dwordx4 v[120:123], v[248:249], off nt
	v_lshl_add_u64 v[248:249], v[248:249], 0, s[98:99]
	ds_read_b128 v[244:247], v128 offset:4352
	s_waitcnt vmcnt(11) lgkmcnt(0)
	v_pk_fma_f32 v[180:181], v[246:247], v[242:243], v[180:181]
	v_pk_fma_f32 v[178:179], v[244:245], v[240:241], v[178:179]
	global_store_dwordx4 v[250:251], v[178:181], off
	v_lshl_add_u64 v[250:251], v[250:251], 0, s[98:99]
	ds_read_b128 v[244:247], v128 offset:5440
	s_waitcnt vmcnt(11) lgkmcnt(0)
	v_pk_fma_f32 v[188:189], v[246:247], v[242:243], v[188:189]
	v_pk_fma_f32 v[186:187], v[244:245], v[240:241], v[186:187]
	global_store_dwordx4 v[250:251], v[186:189], off
	v_lshl_add_u64 v[250:251], v[250:251], 0, s[98:99]
	ds_read_b128 v[244:247], v128 offset:6528
	s_waitcnt vmcnt(11) lgkmcnt(0)
	v_pk_fma_f32 v[192:193], v[246:247], v[242:243], v[192:193]
	v_pk_fma_f32 v[190:191], v[244:245], v[240:241], v[190:191]
	global_store_dwordx4 v[250:251], v[190:193], off
	v_lshl_add_u64 v[250:251], v[250:251], 0, s[98:99]
	ds_read_b128 v[244:247], v128 offset:7616
	s_waitcnt vmcnt(11) lgkmcnt(0)
	v_pk_fma_f32 v[196:197], v[246:247], v[242:243], v[196:197]
	v_pk_fma_f32 v[194:195], v[244:245], v[240:241], v[194:195]
	global_store_dwordx4 v[250:251], v[194:197], off
	v_lshl_add_u64 v[250:251], v[250:251], 0, s[98:99]
	ds_write_b128 v124, v[0:3]
	ds_write_b128 v124, v[4:7] offset:64
	ds_write_b128 v124, v[8:11] offset:128
	ds_write_b128 v124, v[12:15] offset:192
	ds_write_b128 v124, v[16:19] offset:4352
	ds_write_b128 v124, v[20:23] offset:4416
	ds_write_b128 v124, v[24:27] offset:4480
	ds_write_b128 v124, v[28:31] offset:4544
	global_load_dwordx4 v[178:181], v[248:249], off nt
	v_lshl_add_u64 v[248:249], v[248:249], 0, s[98:99]
	global_load_dwordx4 v[186:189], v[248:249], off nt
	v_lshl_add_u64 v[248:249], v[248:249], 0, s[98:99]
	global_load_dwordx4 v[190:193], v[248:249], off nt
	v_lshl_add_u64 v[248:249], v[248:249], 0, s[98:99]
	global_load_dwordx4 v[194:197], v[248:249], off nt
	v_lshl_add_u64 v[248:249], v[248:249], 0, s[98:99]
	ds_read_b128 v[244:247], v128
	s_waitcnt vmcnt(11) lgkmcnt(0)
	v_pk_fma_f32 v[102:103], v[246:247], v[242:243], v[102:103]
	v_pk_fma_f32 v[100:101], v[244:245], v[240:241], v[100:101]
	global_store_dwordx4 v[250:251], v[100:103], off
	v_lshl_add_u64 v[250:251], v[250:251], 0, s[98:99]
	ds_read_b128 v[244:247], v128 offset:1088
	s_waitcnt vmcnt(11) lgkmcnt(0)
	v_pk_fma_f32 v[114:115], v[246:247], v[242:243], v[114:115]
	v_pk_fma_f32 v[112:113], v[244:245], v[240:241], v[112:113]
	global_store_dwordx4 v[250:251], v[112:115], off
	v_lshl_add_u64 v[250:251], v[250:251], 0, s[98:99]
	ds_read_b128 v[244:247], v128 offset:2176
	s_waitcnt vmcnt(11) lgkmcnt(0)
	v_pk_fma_f32 v[118:119], v[246:247], v[242:243], v[118:119]
	v_pk_fma_f32 v[116:117], v[244:245], v[240:241], v[116:117]
	global_store_dwordx4 v[250:251], v[116:119], off
	v_lshl_add_u64 v[250:251], v[250:251], 0, s[98:99]
	ds_read_b128 v[244:247], v128 offset:3264
	s_waitcnt vmcnt(11) lgkmcnt(0)
	v_pk_fma_f32 v[122:123], v[246:247], v[242:243], v[122:123]
	v_pk_fma_f32 v[120:121], v[244:245], v[240:241], v[120:121]
	global_store_dwordx4 v[250:251], v[120:123], off
	v_lshl_add_u64 v[250:251], v[250:251], 0, s[98:99]
	ds_read_b128 v[244:247], v128 offset:4352
	s_waitcnt vmcnt(7) lgkmcnt(0)
	v_pk_fma_f32 v[180:181], v[246:247], v[242:243], v[180:181]
	v_pk_fma_f32 v[178:179], v[244:245], v[240:241], v[178:179]
	global_store_dwordx4 v[250:251], v[178:181], off
	v_lshl_add_u64 v[250:251], v[250:251], 0, s[98:99]
	ds_read_b128 v[244:247], v128 offset:5440
	s_waitcnt vmcnt(7) lgkmcnt(0)
	v_pk_fma_f32 v[188:189], v[246:247], v[242:243], v[188:189]
	v_pk_fma_f32 v[186:187], v[244:245], v[240:241], v[186:187]
	global_store_dwordx4 v[250:251], v[186:189], off
	v_lshl_add_u64 v[250:251], v[250:251], 0, s[98:99]
	ds_read_b128 v[244:247], v128 offset:6528
	s_waitcnt vmcnt(7) lgkmcnt(0)
	v_pk_fma_f32 v[192:193], v[246:247], v[242:243], v[192:193]
	v_pk_fma_f32 v[190:191], v[244:245], v[240:241], v[190:191]
	global_store_dwordx4 v[250:251], v[190:193], off
	v_lshl_add_u64 v[250:251], v[250:251], 0, s[98:99]
	ds_read_b128 v[244:247], v128 offset:7616
	s_waitcnt vmcnt(7) lgkmcnt(0)
	v_pk_fma_f32 v[196:197], v[246:247], v[242:243], v[196:197]
	v_pk_fma_f32 v[194:195], v[244:245], v[240:241], v[194:195]
	global_store_dwordx4 v[250:251], v[194:197], off
	v_lshl_add_u64 v[250:251], v[250:251], 0, s[98:99]
	s_add_i32 s23, s23, s40
	s_cmpk_gt_i32 s23, 0x1ff
	s_cbranch_scc0 .LBB0_1137
